# v8 + prologue: x->fp16 residual conversion (independent of the weight prep) runs before the first grid barrier instead of after it
# baseline (speedup 1.0000x reference)
_Z8hpge_fwd6Params:
	s_load_dwordx8 s[72:79], s[0:1], 0x80
	s_load_dword s3, s[0:1], 0xa0
	s_add_u32 s4, s0, 0xa0
	s_addc_u32 s5, s1, 0
	s_mov_b32 s100, 0
	v_and_b32_e32 v232, 0x3ff, v0
	v_writelane_b32 v254, s4, 0
	v_readfirstlane_b32 s12, v232
	v_cmp_gt_u32_e32 vcc, 16, v232
	v_writelane_b32 v254, s5, 1
	s_and_saveexec_b64 s[4:5], vcc
	v_lshl_add_u32 v1, v232, 2, 0
	v_add_u32_e32 v1, 0x26bc0, v1
	v_mov_b32_e32 v2, 0
	ds_write_b32 v1, v2
	s_or_b64 exec, exec, s[4:5]
	s_waitcnt lgkmcnt(0)
	s_sub_i32 s4, s79, s78
	s_cmp_gt_i32 s4, 1
	s_cselect_b64 s[66:67], -1, 0
	s_cmp_lt_i32 s4, 2
	s_mov_b32 s33, 0
	v_cmp_eq_u32_e32 vcc, 0, v232
	s_mov_b32 s70, 0
	s_barrier
	s_cbranch_scc1 .LBB0_7
	s_getreg_b32 s4, hwreg(HW_REG_XCC_ID, 0, 4)
	s_and_b32 s33, s4, 15
	s_and_saveexec_b64 s[4:5], vcc
	s_cbranch_execz .LBB0_6
	s_mov_b64 s[6:7], exec
	v_mbcnt_lo_u32_b32 v1, s6, 0
	v_mbcnt_hi_u32_b32 v1, s7, v1
	v_cmp_eq_u32_e32 vcc, 0, v1
	s_and_b64 s[8:9], exec, vcc
	s_mov_b64 exec, s[8:9]
	s_cbranch_execz .LBB0_6
	s_lshl_b32 s8, s33, 8
	s_bcnt1_i32_b64 s6, s[6:7]
	v_mov_b32_e32 v1, s8
	v_mov_b32_e32 v2, s6
	global_atomic_add v1, v2, s[76:77] offset:1024

.LBB0_109:
	s_cmp_lg_u32 s100, 0
	s_cbranch_scc1 .Lp0_seam
	s_mov_b32 s100, 1
	s_mov_b64 s[98:99], s[22:23]
	s_branch .Lp0b_pro

.Lp0b_pro:
	v_mov_b32_e32 v73, v233
	s_mov_b32 s31, s2
	v_mov_b32_e32 v124, v232
	s_mov_b32 s0, s71
	s_mov_b32 s30, s3
	s_mov_b64 s[18:19], 0
	s_add_u32 s14, s76, s18
	s_addc_u32 s15, s77, s19
	s_lshl_b32 s26, s31, 3
	s_add_i32 s26, s26, s0
	s_add_u32 s16, s14, 0x100000
	s_addc_u32 s17, s15, 0
	s_cmp_eq_u32 s100, 1
	s_cbranch_scc1 .LBB0_173
	s_cmpk_gt_i32 s26, 0x2ff
	s_cbranch_scc1 .LBB0_173
	v_ashrrev_i32_e32 v2, 4, v73
	v_lshlrev_b32_e32 v0, 3, v2
	v_and_b32_e32 v72, 15, v73
	v_ashrrev_i32_e32 v1, 31, v0
	v_mov_b32_e32 v75, 0
	v_lshl_add_u64 v[76:77], v[0:1], 1, s[16:17]
	v_lshl_add_u64 v[0:1], v[0:1], 2, s[14:15]
	s_mov_b64 s[0:1], 0x2200000
	v_lshlrev_b32_e32 v87, 2, v2
	v_lshlrev_b32_e32 v74, 2, v72
	v_cmp_gt_u32_e32 vcc, 10, v72
	v_lshl_add_u64 v[78:79], v[0:1], 0, s[0:1]
	v_lshl_add_u64 v[0:1], s[14:15], 0, v[74:75]
	s_mov_b64 s[4:5], 0x2300000
	v_or_b32_e32 v74, 1, v87
	v_or_b32_e32 v88, 2, v87
	v_or_b32_e32 v89, 3, v87
	s_lshl_b32 s27, s30, 3
	s_mov_b32 s21, 0
	v_cndmask_b32_e32 v86, 0, v72, vcc
	v_cmp_lt_u32_e64 s[0:1], 9, v72
	v_lshl_add_u64 v[80:81], v[0:1], 0, s[4:5]
	v_cmp_gt_i32_e64 s[10:11], 3, v2
	v_cmp_gt_i32_e64 s[4:5], 10, v74
	v_cmp_gt_i32_e64 s[6:7], 10, v88
	v_cmp_gt_i32_e64 s[8:9], 10, v89
	s_movk_i32 s28, 0x3000
	s_mov_b32 s29, s26
	s_branch .LBB0_163

.LBB0_173:
	s_cmp_eq_u32 s100, 2
	s_cbranch_scc1 .LBB0_194
	s_cmpk_gt_i32 s26, 0x17ff
	s_cbranch_scc1 .LBB0_194
	v_mbcnt_lo_u32_b32 v1, -1, 0
	v_mbcnt_hi_u32_b32 v1, -1, v1
	v_and_b32_e32 v2, 64, v1
	v_add_u32_e32 v2, 64, v2
	v_xor_b32_e32 v3, 1, v1
	v_cmp_lt_i32_e32 vcc, v3, v2
	v_lshlrev_b32_e32 v0, 2, v73
	s_add_u32 s34, s14, 0x2500000
	v_cndmask_b32_e32 v3, v1, v3, vcc
	v_lshlrev_b32_e32 v125, 2, v3
	v_xor_b32_e32 v3, 2, v1
	v_cmp_lt_i32_e32 vcc, v3, v2
	s_addc_u32 s35, s15, 0
	s_lshl_b32 s4, s26, 3
	v_cndmask_b32_e32 v3, v1, v3, vcc
	v_lshlrev_b32_e32 v126, 2, v3
	v_xor_b32_e32 v3, 4, v1
	v_cmp_lt_i32_e32 vcc, v3, v2
	s_lshl_b32 s8, s30, 6
	s_mov_b64 s[10:11], 0x2800000
	v_cndmask_b32_e32 v3, v1, v3, vcc
	v_lshlrev_b32_e32 v127, 2, v3
	v_xor_b32_e32 v3, 8, v1
	v_cmp_lt_i32_e32 vcc, v3, v2
	s_ashr_i32 s5, s4, 31
	s_ashr_i32 s9, s8, 31
	v_cndmask_b32_e32 v3, v1, v3, vcc
	v_lshlrev_b32_e32 v128, 2, v3
	v_xor_b32_e32 v3, 16, v1
	v_cmp_lt_i32_e32 vcc, v3, v2
	v_add_u32_e32 v4, 0x200, v0
	v_add_u32_e32 v6, 0x300, v0
	v_cndmask_b32_e32 v3, v1, v3, vcc
	v_lshlrev_b32_e32 v129, 2, v3
	v_xor_b32_e32 v3, 32, v1
	v_cmp_lt_i32_e32 vcc, v3, v2
	v_add_u32_e32 v2, 0x100, v0
	v_ashrrev_i32_e32 v5, 31, v4
	v_cndmask_b32_e32 v1, v1, v3, vcc
	v_lshlrev_b32_e32 v130, 2, v1
	v_ashrrev_i32_e32 v1, 31, v0
	v_lshlrev_b64 v[8:9], 1, v[0:1]
	v_lshl_add_u64 v[10:11], s[14:15], 0, v[8:9]
	v_lshl_add_u64 v[112:113], v[10:11], 0, s[10:11]
	s_lshl_b64 s[10:11], s[4:5], 12
	s_add_u32 s10, s36, s10
	s_addc_u32 s11, s37, s11
	s_lshl_b64 s[20:21], s[8:9], 12
	s_lshl_b64 s[22:23], s[4:5], 2
	s_add_u32 s36, s76, s22
	s_addc_u32 s37, s77, s23
	s_lshl_b64 s[22:23], s[8:9], 2
	s_lshl_b64 s[24:25], s[4:5], 11
	s_add_u32 s24, s76, s24
	v_ashrrev_i32_e32 v3, 31, v2
	v_ashrrev_i32_e32 v7, 31, v6
	s_addc_u32 s25, s77, s25
	s_mov_b32 s7, 0
	v_cmp_eq_u32_e64 s[0:1], 0, v73
	v_lshl_add_u64 v[114:115], s[24:25], 0, v[8:9]
	s_lshl_b64 s[24:25], s[8:9], 11
	v_lshlrev_b64 v[116:117], 2, v[0:1]
	v_lshlrev_b64 v[118:119], 2, v[2:3]
	v_lshlrev_b64 v[120:121], 2, v[4:5]
	v_lshlrev_b64 v[122:123], 2, v[6:7]
	v_mov_b32_e32 v131, 0
	v_mov_b32_e32 v132, 0x2500000
	s_branch .LBB0_176

.LBB0_194:
	s_cmp_eq_u32 s100, 1
	s_cbranch_scc0 .Lp0_d
	s_mov_b32 s100, 2
	s_mov_b64 s[22:23], s[98:99]
	s_branch .LBB0_109
